# s6 LN-stat exchange: dropped redundant per-panel buffer_wbl2/buffer_inv (stats use sc1 stores + sc1 loads, drained by vmcnt(0)+barrier before the counter atomic)
# speedup vs baseline: 1.0693x; 1.0155x over previous
.LBB0_349:
	s_or_b64 exec, exec, s[4:5]
	s_waitcnt vmcnt(0)
	v_cmp_eq_u32_e32 vcc, 0, v32
	s_barrier
	s_and_saveexec_b64 s[4:5], vcc
	s_cbranch_execz .LBB0_361
	s_lshl_b32 s6, s24, 6
	s_ashr_i32 s7, s6, 31
	s_lshl_b64 s[6:7], s[6:7], 2
	v_readlane_b32 s8, v254, 11
	v_readlane_b32 s9, v254, 12
	s_add_u32 s8, s8, s6
	s_addc_u32 s9, s9, s7
	s_ashr_i32 s83, s82, 31
	s_lshl_b64 s[6:7], s[82:83], 2
	s_add_u32 s6, s8, s6
	s_addc_u32 s7, s9, s7
	s_mov_b64 s[8:9], exec
	v_mbcnt_lo_u32_b32 v34, s8, 0
	v_mbcnt_hi_u32_b32 v34, s9, v34
	v_cmp_eq_u32_e32 vcc, 0, v34
	s_and_saveexec_b64 s[10:11], vcc
	s_cbranch_execz .LBB0_352
	s_bcnt1_i32_b64 s8, s[8:9]
	v_mov_b32_e32 v34, s8
	s_waitcnt vmcnt(0)
	global_atomic_add v177, v34, s[6:7]

.LBB0_354:
	global_load_dword v34, v177, s[6:7] sc1
	s_mov_b64 s[8:9], -1
	s_waitcnt vmcnt(0)
	v_cmp_lt_u32_e32 vcc, 3, v34
	s_cbranch_vccnz .LBB0_353
	s_sleep 1
	global_load_dword v34, v177, s[6:7] sc1
	s_waitcnt vmcnt(0)
	v_cmp_gt_u32_e32 vcc, 4, v34
	s_cbranch_vccz .LBB0_353
	s_sleep 1
	global_load_dword v34, v177, s[6:7] sc1
	s_waitcnt vmcnt(0)
	v_cmp_gt_u32_e32 vcc, 4, v34
	s_cbranch_vccz .LBB0_353
	s_sleep 1
	global_load_dword v34, v177, s[6:7] sc1
	s_waitcnt vmcnt(0)
	v_cmp_gt_u32_e32 vcc, 4, v34
	s_cbranch_vccz .LBB0_353
	s_sleep 1
	global_load_dword v34, v177, s[6:7] sc1
	s_waitcnt vmcnt(0)
	v_cmp_gt_u32_e32 vcc, 4, v34
	s_cbranch_vccz .LBB0_353
	s_add_i32 s10, s10, -5
	s_cmp_eq_u32 s10, 0
	s_cselect_b64 s[8:9], -1, 0
	s_sleep 1
	s_branch .LBB0_353
.LBB0_360:
	s_waitcnt vmcnt(0)
.LBB0_361:
	s_or_b64 exec, exec, s[4:5]
	s_barrier
	s_and_saveexec_b64 s[4:5], s[36:37]
	s_cbranch_execz .LBB0_363
	s_lshl_b32 s6, s82, 2
	s_ashr_i32 s7, s6, 31
	v_lshl_add_u64 v[34:35], v[32:33], 3, s[2:3]
	s_lshl_b64 s[2:3], s[6:7], 11
	v_lshl_add_u64 v[194:195], v[34:35], 0, s[2:3]
	global_load_dwordx2 v[220:221], v[194:195], off sc1
	s_or_b32 s2, s6, 1
	s_ashr_i32 s3, s2, 31
	s_lshl_b64 s[2:3], s[2:3], 11
	v_lshlrev_b32_e32 v32, 3, v32
	v_lshl_add_u64 v[194:195], v[34:35], 0, s[2:3]
	global_load_dwordx2 v[222:223], v[194:195], off sc1
	s_or_b32 s2, s6, 2
	s_ashr_i32 s3, s2, 31
	s_lshl_b64 s[2:3], s[2:3], 11
	v_lshl_add_u64 v[194:195], v[34:35], 0, s[2:3]
	s_or_b32 s2, s6, 3
	s_ashr_i32 s3, s2, 31
	s_lshl_b64 s[2:3], s[2:3], 11
	global_load_dwordx2 v[194:195], v[194:195], off sc1
	v_lshl_add_u64 v[34:35], v[34:35], 0, s[2:3]
	global_load_dwordx2 v[34:35], v[34:35], off sc1
	s_mov_b32 s2, 0x3a800000
	s_waitcnt vmcnt(3)
	v_add_f32_e32 v33, 0, v220
	v_add_f32_e32 v176, 0, v221
	s_waitcnt vmcnt(2)
	v_add_f32_e32 v33, v33, v222
	v_add_f32_e32 v176, v176, v223
	s_waitcnt vmcnt(1)
	v_add_f32_e32 v33, v33, v194
	v_add_f32_e32 v176, v176, v195
	s_waitcnt vmcnt(0)
	v_add_f32_e32 v33, v33, v34
	v_mul_f32_e32 v34, 0x3a800000, v33
	v_add_f32_e32 v35, v176, v35
	v_mul_f32_e32 v33, v34, v34
	v_fma_f32 v33, v35, s2, -v33
	v_max_f32_e32 v33, 0, v33
	v_add_f32_e32 v33, 0x3727c5ac, v33
	s_mov_b32 s2, 0x800000
	v_cmp_gt_f32_e32 vcc, s2, v33
	v_mul_f32_e32 v35, 0x4b800000, v33
	s_nop 0
	v_cndmask_b32_e32 v33, v33, v35, vcc
	v_rsq_f32_e32 v33, v33
	s_nop 0
	v_mul_f32_e32 v35, 0x45800000, v33
	v_cndmask_b32_e32 v35, v33, v35, vcc
	ds_write_b64 v32, v[34:35] offset:8192
